# v65 plus DSW score tiles: the 4 K-fragment LDS reads of a tile issued together (2 unused quads) with counted lgkmcnt waits
# speedup vs baseline: 1.0057x; 1.0022x over previous
; #define LAS __attribute__((address_space(3)))
; template <int L>
; __device__ __forceinline__ void layer_body(const Args& args, LAS unsigned char* lds, const int wave, const int G, const int gw, const int NGW, const int lo, const int hi,
;                                            unsigned char* const ws_kernel, const XcdBarrier& bar, int& pid) {
;     ...
; #pragma unroll
;                     for (int t = 0; t < 10; ++t) {
;                         const int T = wave + t, Tc = min(T, 15);
;                         const unsigned ka = Kimg + (unsigned)((16 * Tc + qi) * KPITCH + 16 * kg);
;                         f32x4 a = (f32x4){0.f, 0.f, 0.f, 0.f};
; #pragma unroll
;                         for (int ks = 0; ks < 4; ++ks) a = __builtin_amdgcn_mfma_f32_16x16x32_bf16(*(const LAS bf16x8*)(size_t)(ka + 64 * ks), qfn[ks], a, 0, 0, 0);
; #pragma unroll
;                         for (int j = 0; j < 4; ++j) { const int m = ms - 64 + 16 * T + 4 * kg + j, dd = m - mq; const bool valid = (m >= 0) && (m < Lc) && (dd >= -64) && (dd <= 64);
;                             sc[t][j] = valid ? a[j] * scale_log2 : -1e30f; }
;                         __builtin_amdgcn_sched_barrier(0);
;                     }
;                     if (unit + GH < UEND) DSW_LOADQ(unit + GH);
.LBB0_1712:
	v_or_b32_e32 v88, s38, v123
	v_mad_u32_u24 v88, v88, s56, v90
	ds_read_b128 v[92:95], v88
	ds_read_b128 v[96:99], v88 offset:64
	ds_read_b128 v[184:187], v88 offset:128
	ds_read_b128 v[188:191], v88 offset:192
	s_waitcnt lgkmcnt(3)
	v_mfma_f32_16x16x32_bf16 v[92:95], v[92:95], v[40:43], 0
	s_waitcnt lgkmcnt(2)
	v_mfma_f32_16x16x32_bf16 v[92:95], v[96:99], v[44:47], v[92:95]
	s_waitcnt lgkmcnt(1)
	v_mfma_f32_16x16x32_bf16 v[92:95], v[184:187], v[48:51], v[92:95]
	s_waitcnt lgkmcnt(0)
	v_mfma_f32_16x16x32_bf16 v[108:111], v[188:191], v[52:55], v[92:95]
	v_or_b32_e32 v88, s40, v123
	v_mad_u32_u24 v88, v88, s56, v90
	s_nop 2
	ds_read_b128 v[92:95], v88
	ds_read_b128 v[96:99], v88 offset:64
	ds_read_b128 v[184:187], v88 offset:128
	ds_read_b128 v[188:191], v88 offset:192
	s_waitcnt lgkmcnt(3)
	v_mfma_f32_16x16x32_bf16 v[92:95], v[92:95], v[40:43], 0
	s_waitcnt lgkmcnt(2)
	v_mfma_f32_16x16x32_bf16 v[92:95], v[96:99], v[44:47], v[92:95]
	s_waitcnt lgkmcnt(1)
	v_mfma_f32_16x16x32_bf16 v[92:95], v[184:187], v[48:51], v[92:95]
	s_waitcnt lgkmcnt(0)
	v_mfma_f32_16x16x32_bf16 v[104:107], v[188:191], v[52:55], v[92:95]
	v_or_b32_e32 v88, s42, v123
	v_mad_u32_u24 v88, v88, s56, v90
	s_nop 2
	ds_read_b128 v[92:95], v88
	ds_read_b128 v[96:99], v88 offset:64
	ds_read_b128 v[184:187], v88 offset:128
	ds_read_b128 v[188:191], v88 offset:192
	s_waitcnt lgkmcnt(3)
	v_mfma_f32_16x16x32_bf16 v[92:95], v[92:95], v[40:43], 0
	s_waitcnt lgkmcnt(2)
	v_mfma_f32_16x16x32_bf16 v[92:95], v[96:99], v[44:47], v[92:95]
	s_waitcnt lgkmcnt(1)
	v_mfma_f32_16x16x32_bf16 v[92:95], v[184:187], v[48:51], v[92:95]
	s_waitcnt lgkmcnt(0)
	v_mfma_f32_16x16x32_bf16 v[100:103], v[188:191], v[52:55], v[92:95]
	v_or_b32_e32 v88, s44, v123
	v_mad_u32_u24 v88, v88, s56, v90
	s_nop 2
	ds_read_b128 v[92:95], v88
	ds_read_b128 v[96:99], v88 offset:64
	ds_read_b128 v[184:187], v88 offset:128
	ds_read_b128 v[188:191], v88 offset:192
	s_waitcnt lgkmcnt(3)
	v_mfma_f32_16x16x32_bf16 v[92:95], v[92:95], v[40:43], 0
	s_waitcnt lgkmcnt(2)
	v_mfma_f32_16x16x32_bf16 v[92:95], v[96:99], v[44:47], v[92:95]
	s_waitcnt lgkmcnt(1)
	v_mfma_f32_16x16x32_bf16 v[92:95], v[184:187], v[48:51], v[92:95]
	s_waitcnt lgkmcnt(0)
	v_mfma_f32_16x16x32_bf16 v[96:99], v[188:191], v[52:55], v[92:95]
	v_or_b32_e32 v88, s46, v123
	v_mad_u32_u24 v88, v88, s56, v90
	s_nop 2
	ds_read_b128 v[92:95], v88
	ds_read_b128 v[136:139], v88 offset:64
	ds_read_b128 v[184:187], v88 offset:128
	ds_read_b128 v[188:191], v88 offset:192
	s_waitcnt lgkmcnt(3)
	v_mfma_f32_16x16x32_bf16 v[92:95], v[92:95], v[40:43], 0
	s_waitcnt lgkmcnt(2)
	v_mfma_f32_16x16x32_bf16 v[92:95], v[136:139], v[44:47], v[92:95]
	s_waitcnt lgkmcnt(1)
	v_mfma_f32_16x16x32_bf16 v[92:95], v[184:187], v[48:51], v[92:95]
	s_waitcnt lgkmcnt(0)
	v_mfma_f32_16x16x32_bf16 v[92:95], v[188:191], v[52:55], v[92:95]
	v_or_b32_e32 v88, s48, v123
	v_mad_u32_u24 v112, v88, s56, v90
	ds_read_b128 v[88:91], v112
	ds_read_b128 v[136:139], v112 offset:64
	ds_read_b128 v[184:187], v112 offset:128
	ds_read_b128 v[188:191], v112 offset:192
	s_waitcnt lgkmcnt(3)
	v_mfma_f32_16x16x32_bf16 v[88:91], v[88:91], v[40:43], 0
	s_waitcnt lgkmcnt(2)
	v_mfma_f32_16x16x32_bf16 v[88:91], v[136:139], v[44:47], v[88:91]
	s_waitcnt lgkmcnt(1)
	v_mfma_f32_16x16x32_bf16 v[88:91], v[184:187], v[48:51], v[88:91]
	s_waitcnt lgkmcnt(0)
	v_mfma_f32_16x16x32_bf16 v[88:91], v[188:191], v[52:55], v[88:91]
	s_andn2_b64 vcc, exec, s[68:69]
	s_cbranch_vccnz .LBB0_1714
	s_ashr_i32 s3, s80, 4
	s_mul_hi_i32 s4, s3, 0x55555556
	s_lshr_b32 s5, s4, 31
	s_add_i32 s4, s4, s5
	s_mul_i32 s5, s4, 3
	s_and_b32 s2, s80, 15
	s_sub_i32 s3, s3, s5
	s_cmp_eq_u32 s3, 1
	s_cselect_b32 s5, 2, 4
	s_cmp_lg_u32 s3, 0
	s_cselect_b32 s5, s5, 0
	s_lshr_b32 s68, 16, s5
	s_sub_i32 s69, 4, s5
	s_add_i32 s68, s68, -1
	s_lshr_b32 s69, s2, s69
	s_and_b32 s2, s68, s2
	s_lshl_b32 s68, s2, 7
	s_mul_i32 s2, s3, 0x1800
	s_ashr_i32 s3, s2, 31
	s_lshl_b64 s[2:3], s[2:3], 1
	s_add_u32 s2, s8, s2
	s_addc_u32 s3, s9, s3
	s_lshl_b32 s85, s4, 7
	s_lshl_b32 s4, s4, 8
	s_and_b32 s4, s4, 0xf00
	s_add_u32 s2, s2, s4
	s_addc_u32 s3, s3, 0
	s_add_i32 s68, s68, s1
	s_and_b32 s4, s85, 0xfffff800
	v_or_b32_e32 v40, s68, v123
	v_lshlrev_b32_e32 v40, s5, v40
	s_or_b32 s4, s69, s4
	v_add_u32_e32 v42, s4, v40
	v_mov_b64_e32 v[40:41], s[2:3]
	v_mad_i64_i32 v[40:41], s[2:3], v42, s57, v[40:41]
	v_lshlrev_b32_e32 v112, 4, v119
	v_lshl_add_u64 v[52:53], v[40:41], 0, v[112:113]
	global_load_dwordx4 v[40:43], v[52:53], off
	global_load_dwordx4 v[44:47], v[52:53], off offset:64
	global_load_dwordx4 v[48:51], v[52:53], off offset:128
	s_nop 0
	global_load_dwordx4 v[52:55], v[52:53], off offset:192
